# hand-written sequential unmasked selected-pair body with scalar softmax (control for the packed variant)
# speedup vs baseline: 1.0119x; 1.0119x over previous
.LBB0_1046:
	s_andn2_b64 vcc, exec, s[22:23]
	s_cbranch_vccnz .LBB0_1048
	s_mov_b32 s30, 0x3e38aa3b
	s_mov_b32 s31, 0x3e38aa3b
	s_mov_b32 s29, s28
	s_sub_i32 s22, s81, 64
	s_and_b32 s22, s22, 0xc0
	s_mulk_i32 s22, 0xa0
	v_add_u32_e32 v193, s22, v153
	s_waitcnt lgkmcnt(7)
	v_mfma_f32_16x16x32_bf16 v[0:3], v[88:91], v[60:63], 0
	s_waitcnt lgkmcnt(5)
	v_mfma_f32_16x16x32_bf16 v[4:7], v[96:99], v[60:63], 0
	s_waitcnt lgkmcnt(3)
	v_mfma_f32_16x16x32_bf16 v[8:11], v[104:107], v[60:63], 0
	s_waitcnt lgkmcnt(1)
	v_mfma_f32_16x16x32_bf16 v[12:15], v[112:115], v[60:63], 0
	v_mfma_f32_16x16x32_bf16 v[0:3], v[92:95], v[56:59], v[0:3]
	v_mfma_f32_16x16x32_bf16 v[4:7], v[100:103], v[56:59], v[4:7]
	v_mfma_f32_16x16x32_bf16 v[8:11], v[108:111], v[56:59], v[8:11]
	s_waitcnt lgkmcnt(0)
	v_mfma_f32_16x16x32_bf16 v[12:15], v[116:119], v[56:59], v[12:15]
	s_setprio 0
	ds_read_b128 v[88:91], v143 offset:40960
	ds_read_b128 v[92:95], v143 offset:43520
	ds_read_b128 v[96:99], v143 offset:46080
	ds_read_b128 v[100:103], v143 offset:48640
	ds_read_b128 v[104:107], v143 offset:41024
	ds_read_b128 v[108:111], v143 offset:43584
	ds_read_b128 v[112:115], v143 offset:46144
	ds_read_b128 v[116:119], v143 offset:48704
	ds_read_b128 v[194:197], v193
	ds_read_b128 v[198:201], v193 offset:64
	ds_read_b128 v[202:205], v193 offset:2560
	ds_read_b128 v[206:209], v193 offset:2624
	ds_read_b128 v[210:213], v193 offset:5120
	ds_read_b128 v[214:217], v193 offset:5184
	ds_read_b128 v[218:221], v193 offset:7680
	v_mul_f32_e64 v226, -v146, v147
	v_cndmask_b32_e64 v226, v179, v226, s[20:21]
	v_add_f32_e32 v227, v192, v226
	v_add_f32_e32 v228, v146, v227
	v_add_f32_e32 v229, v137, v227
	v_add_f32_e32 v230, v188, v227
	v_fmamk_f32 v0, v0, 0x3e38aa3b, v227
	v_fmamk_f32 v1, v1, 0x3e38aa3b, v228
	v_fmamk_f32 v2, v2, 0x3e38aa3b, v229
	v_fmamk_f32 v3, v3, 0x3e38aa3b, v230
	v_exp_f32_e32 v0, v0
	v_exp_f32_e32 v1, v1
	v_exp_f32_e32 v2, v2
	v_exp_f32_e32 v3, v3
	v_add_f32_e32 v227, v189, v226
	v_add_f32_e32 v228, v146, v227
	v_add_f32_e32 v229, v137, v227
	v_add_f32_e32 v230, v188, v227
	v_fmamk_f32 v4, v4, 0x3e38aa3b, v227
	v_fmamk_f32 v5, v5, 0x3e38aa3b, v228
	v_fmamk_f32 v6, v6, 0x3e38aa3b, v229
	v_fmamk_f32 v7, v7, 0x3e38aa3b, v230
	v_exp_f32_e32 v4, v4
	v_exp_f32_e32 v5, v5
	v_exp_f32_e32 v6, v6
	v_exp_f32_e32 v7, v7
	v_add_f32_e32 v227, v190, v226
	v_add_f32_e32 v228, v146, v227
	v_add_f32_e32 v229, v137, v227
	v_add_f32_e32 v230, v188, v227
	v_fmamk_f32 v8, v8, 0x3e38aa3b, v227
	v_fmamk_f32 v9, v9, 0x3e38aa3b, v228
	v_fmamk_f32 v10, v10, 0x3e38aa3b, v229
	v_fmamk_f32 v11, v11, 0x3e38aa3b, v230
	v_exp_f32_e32 v8, v8
	v_exp_f32_e32 v9, v9
	v_exp_f32_e32 v10, v10
	v_exp_f32_e32 v11, v11
	v_add_f32_e32 v227, v191, v226
	v_add_f32_e32 v228, v146, v227
	v_add_f32_e32 v229, v137, v227
	v_add_f32_e32 v230, v188, v227
	v_fmamk_f32 v12, v12, 0x3e38aa3b, v227
	v_fmamk_f32 v13, v13, 0x3e38aa3b, v228
	v_fmamk_f32 v14, v14, 0x3e38aa3b, v229
	v_fmamk_f32 v15, v15, 0x3e38aa3b, v230
	v_exp_f32_e32 v12, v12
	v_exp_f32_e32 v13, v13
	v_exp_f32_e32 v14, v14
	v_exp_f32_e32 v15, v15
	v_cvt_pk_bf16_f32 v226, v0, v1
	v_cvt_pk_bf16_f32 v227, v2, v3
	v_cvt_pk_bf16_f32 v228, v4, v5
	v_cvt_pk_bf16_f32 v229, v6, v7
	v_cvt_pk_bf16_f32 v230, v8, v9
	v_cvt_pk_bf16_f32 v231, v10, v11
	v_cvt_pk_bf16_f32 v232, v12, v13
	v_cvt_pk_bf16_f32 v233, v14, v15
	s_nop 1
	s_setprio 1
	s_waitcnt lgkmcnt(14)
	v_mfma_f32_16x16x32_bf16 v[0:3], v[88:91], v[226:229], v[36:39]
	ds_read_b128 v[222:225], v193 offset:7744
	s_waitcnt lgkmcnt(14)
	v_mfma_f32_16x16x32_bf16 v[4:7], v[92:95], v[226:229], v[40:43]
	s_waitcnt lgkmcnt(13)
	v_mfma_f32_16x16x32_bf16 v[8:11], v[96:99], v[226:229], v[44:47]
	s_waitcnt lgkmcnt(12)
	v_mfma_f32_16x16x32_bf16 v[12:15], v[100:103], v[226:229], v[84:87]
	v_pk_mov_b32 v[36:37], s[28:29], s[28:29] op_sel:[0,1]
	v_pk_mov_b32 v[38:39], s[28:29], s[28:29] op_sel:[0,1]
	s_nop 1
	v_mfma_f32_16x16x32_bf16 v[80:83], v[36:39], v[226:229], v[32:35]
	s_waitcnt lgkmcnt(11)
	v_mfma_f32_16x16x32_bf16 v[0:3], v[104:107], v[230:233], v[0:3]
	s_waitcnt lgkmcnt(10)
	v_mfma_f32_16x16x32_bf16 v[4:7], v[108:111], v[230:233], v[4:7]
	s_waitcnt lgkmcnt(9)
	v_mfma_f32_16x16x32_bf16 v[8:11], v[112:115], v[230:233], v[8:11]
	s_waitcnt lgkmcnt(8)
	v_mfma_f32_16x16x32_bf16 v[12:15], v[116:119], v[230:233], v[12:15]
	v_mfma_f32_16x16x32_bf16 v[80:83], v[36:39], v[230:233], v[80:83]
	s_waitcnt lgkmcnt(7)
	v_mfma_f32_16x16x32_bf16 v[36:39], v[194:197], v[60:63], 0
	s_waitcnt lgkmcnt(5)
	v_mfma_f32_16x16x32_bf16 v[40:43], v[202:205], v[60:63], 0
	s_waitcnt lgkmcnt(3)
	v_mfma_f32_16x16x32_bf16 v[44:47], v[210:213], v[60:63], 0
	s_waitcnt lgkmcnt(1)
	v_mfma_f32_16x16x32_bf16 v[84:87], v[218:221], v[60:63], 0
	v_mfma_f32_16x16x32_bf16 v[36:39], v[198:201], v[56:59], v[36:39]
	v_mfma_f32_16x16x32_bf16 v[40:43], v[206:209], v[56:59], v[40:43]
	v_mfma_f32_16x16x32_bf16 v[44:47], v[214:217], v[56:59], v[44:47]
	s_waitcnt lgkmcnt(0)
	v_mfma_f32_16x16x32_bf16 v[84:87], v[222:225], v[56:59], v[84:87]
	s_setprio 0
	ds_read_b128 v[194:197], v193 offset:40960
	ds_read_b128 v[198:201], v193 offset:43520
	ds_read_b128 v[202:205], v193 offset:46080
	ds_read_b128 v[206:209], v193 offset:48640
	ds_read_b128 v[210:213], v193 offset:41024
	ds_read_b128 v[214:217], v193 offset:43584
	ds_read_b128 v[218:221], v193 offset:46144
	ds_read_b128 v[222:225], v193 offset:48704
	v_mul_f32_e64 v226, -v146, v141
	v_cndmask_b32_e64 v226, v179, v226, s[0:1]
	v_add_f32_e32 v227, v192, v226
	v_add_f32_e32 v228, v146, v227
	v_add_f32_e32 v229, v137, v227
	v_add_f32_e32 v230, v188, v227
	v_fmamk_f32 v36, v36, 0x3e38aa3b, v227
	v_fmamk_f32 v37, v37, 0x3e38aa3b, v228
	v_fmamk_f32 v38, v38, 0x3e38aa3b, v229
	v_fmamk_f32 v39, v39, 0x3e38aa3b, v230
	v_exp_f32_e32 v36, v36
	v_exp_f32_e32 v37, v37
	v_exp_f32_e32 v38, v38
	v_exp_f32_e32 v39, v39
	v_add_f32_e32 v227, v189, v226
	v_add_f32_e32 v228, v146, v227
	v_add_f32_e32 v229, v137, v227
	v_add_f32_e32 v230, v188, v227
	v_fmamk_f32 v40, v40, 0x3e38aa3b, v227
	v_fmamk_f32 v41, v41, 0x3e38aa3b, v228
	v_fmamk_f32 v42, v42, 0x3e38aa3b, v229
	v_fmamk_f32 v43, v43, 0x3e38aa3b, v230
	v_exp_f32_e32 v40, v40
	v_exp_f32_e32 v41, v41
	v_exp_f32_e32 v42, v42
	v_exp_f32_e32 v43, v43
	v_add_f32_e32 v227, v190, v226
	v_add_f32_e32 v228, v146, v227
	v_add_f32_e32 v229, v137, v227
	v_add_f32_e32 v230, v188, v227
	v_fmamk_f32 v44, v44, 0x3e38aa3b, v227
	v_fmamk_f32 v45, v45, 0x3e38aa3b, v228
	v_fmamk_f32 v46, v46, 0x3e38aa3b, v229
	v_fmamk_f32 v47, v47, 0x3e38aa3b, v230
	v_exp_f32_e32 v44, v44
	v_exp_f32_e32 v45, v45
	v_exp_f32_e32 v46, v46
	v_exp_f32_e32 v47, v47
	v_add_f32_e32 v227, v191, v226
	v_add_f32_e32 v228, v146, v227
	v_add_f32_e32 v229, v137, v227
	v_add_f32_e32 v230, v188, v227
	v_fmamk_f32 v84, v84, 0x3e38aa3b, v227
	v_fmamk_f32 v85, v85, 0x3e38aa3b, v228
	v_fmamk_f32 v86, v86, 0x3e38aa3b, v229
	v_fmamk_f32 v87, v87, 0x3e38aa3b, v230
	v_exp_f32_e32 v84, v84
	v_exp_f32_e32 v85, v85
	v_exp_f32_e32 v86, v86
	v_exp_f32_e32 v87, v87
	v_cvt_pk_bf16_f32 v88, v36, v37
	v_cvt_pk_bf16_f32 v89, v38, v39
	v_cvt_pk_bf16_f32 v90, v40, v41
	v_cvt_pk_bf16_f32 v91, v42, v43
	v_cvt_pk_bf16_f32 v92, v44, v45
	v_cvt_pk_bf16_f32 v93, v46, v47
	v_cvt_pk_bf16_f32 v94, v84, v85
	v_cvt_pk_bf16_f32 v95, v86, v87
	v_pk_mov_b32 v[96:97], s[28:29], s[28:29] op_sel:[0,1]
	v_pk_mov_b32 v[98:99], s[28:29], s[28:29] op_sel:[0,1]
	s_nop 1
	s_setprio 1
	s_waitcnt lgkmcnt(7)
	v_mfma_f32_16x16x32_bf16 v[0:3], v[194:197], v[88:91], v[0:3]
	s_waitcnt lgkmcnt(6)
	v_mfma_f32_16x16x32_bf16 v[4:7], v[198:201], v[88:91], v[4:7]
	s_waitcnt lgkmcnt(5)
	v_mfma_f32_16x16x32_bf16 v[8:11], v[202:205], v[88:91], v[8:11]
	s_waitcnt lgkmcnt(4)
	v_mfma_f32_16x16x32_bf16 v[12:15], v[206:209], v[88:91], v[12:15]
	v_mfma_f32_16x16x32_bf16 v[80:83], v[96:99], v[88:91], v[80:83]
	s_waitcnt lgkmcnt(3)
	v_mfma_f32_16x16x32_bf16 v[0:3], v[210:213], v[92:95], v[0:3]
	s_waitcnt lgkmcnt(2)
	v_mfma_f32_16x16x32_bf16 v[4:7], v[214:217], v[92:95], v[4:7]
	s_waitcnt lgkmcnt(1)
	v_mfma_f32_16x16x32_bf16 v[8:11], v[218:221], v[92:95], v[8:11]
	s_waitcnt lgkmcnt(0)
	v_mfma_f32_16x16x32_bf16 v[12:15], v[222:225], v[92:95], v[12:15]
	v_mfma_f32_16x16x32_bf16 v[80:83], v[96:99], v[92:95], v[80:83]
